# P4 wg2/wu2 fp8 copies written by hand: register + ds_bpermute transposition, no LDS image or barriers, two items in flight (normal P4 order)
# speedup vs baseline: 1.0021x; 1.0021x over previous
.LBB0_603:
	s_or_b64 exec, exec, s[6:7]
	s_waitcnt lgkmcnt(0)
	s_barrier
	v_mbcnt_lo_u32_b32 v234, -1, 0
	v_mbcnt_hi_u32_b32 v234, -1, v234
	s_mov_b32 s98, 0
.Lp4_copy_entry:
	s_load_dwordx2 s[40:41], s[0:1], 0x70
	s_load_dwordx4 s[60:63], s[0:1], 0x78
	s_lshr_b32 s77, s91, 2
	s_lshl_b32 s77, s77, 2
	s_add_i32 s77, s77, s91
	s_lshl_b32 s77, s77, 16
	v_lshrrev_b32_e32 v196, 3, v234
	v_and_b32_e32 v197, 7, v234
	v_mul_u32_u24_e32 v195, 0x58000, v196
	v_lshl_add_u32 v195, v197, 4, v195
	v_lshlrev_b32_e32 v199, 6, v196
	v_lshl_add_u32 v198, v197, 3, v196
	v_lshlrev_b32_e32 v198, 2, v198
	v_lshlrev_b32_e32 v196, 13, v196
	v_lshl_add_u32 v196, v197, 4, v196
	v_add_u32_e32 v197, 0x1000, v196
	v_mov_b32_e32 v192, 0x44800000
	v_mov_b32_e32 v193, 0x43e00000
	v_mov_b32_e32 v194, 0xc3e00000
	s_waitcnt lgkmcnt(0)
	s_mov_b32 s44, s2
	s_cmpk_ge_u32 s44, 0x160
	s_cselect_b32 s45, 1, 0
	s_mul_i32 s67, s45, 0x160
	s_sub_i32 s44, s44, s67
	s_mul_i32 s67, s44, 2979
	s_lshr_b32 s67, s67, 16
	s_mul_i32 s69, s67, 22
	s_sub_i32 s69, s44, s69
	s_lshl_b32 s67, s67, 7
	s_cmp_eq_u32 s45, 0
	s_cselect_b32 s20, s60, s62
	s_cselect_b32 s21, s61, s63
	s_mul_i32 s76, s67, 0x5800
	s_lshl_b32 s44, s69, 10
	s_add_i32 s76, s76, s44
	s_lshl_b32 s44, s91, 7
	s_add_i32 s76, s76, s44
	s_add_u32 s20, s20, s76
	s_addc_u32 s21, s21, 0
	s_lshl_b32 s44, s67, 2
	s_add_u32 s34, s40, s44
	s_addc_u32 s35, s41, 0
	s_lshl_b32 s44, s69, 20
	s_lshl_b32 s45, s45, 18
	s_add_i32 s44, s44, s45
	s_add_i32 s44, s44, s67
	s_add_i32 s44, s44, s77
	s_add_u32 s26, s50, s44
	s_addc_u32 s27, s51, 0
	s_add_u32 s26, s26, 0x6300000
	s_addc_u32 s27, s27, 0
	s_add_i32 s44, s2, 256
	s_cmpk_ge_u32 s44, 0x160
	s_cselect_b32 s45, 1, 0
	s_mul_i32 s67, s45, 0x160
	s_sub_i32 s44, s44, s67
	s_mul_i32 s67, s44, 2979
	s_lshr_b32 s67, s67, 16
	s_mul_i32 s69, s67, 22
	s_sub_i32 s69, s44, s69
	s_lshl_b32 s67, s67, 7
	s_cmp_eq_u32 s45, 0
	s_cselect_b32 s22, s60, s62
	s_cselect_b32 s23, s61, s63
	s_mul_i32 s76, s67, 0x5800
	s_lshl_b32 s44, s69, 10
	s_add_i32 s76, s76, s44
	s_lshl_b32 s44, s91, 7
	s_add_i32 s76, s76, s44
	s_add_u32 s22, s22, s76
	s_addc_u32 s23, s23, 0
	s_lshl_b32 s44, s67, 2
	s_add_u32 s36, s40, s44
	s_addc_u32 s37, s41, 0
	s_lshl_b32 s44, s69, 20
	s_lshl_b32 s45, s45, 18
	s_add_i32 s44, s44, s45
	s_add_i32 s44, s44, s67
	s_add_i32 s44, s44, s77
	s_add_u32 s28, s50, s44
	s_addc_u32 s29, s51, 0
	s_add_u32 s28, s28, 0x6300000
	s_addc_u32 s29, s29, 0
	global_load_dwordx4 v[64:67], v199, s[34:35] offset:0
	global_load_dwordx4 v[68:71], v199, s[34:35] offset:16
	global_load_dwordx4 v[72:75], v199, s[34:35] offset:32
	global_load_dwordx4 v[76:79], v199, s[34:35] offset:48
	global_load_dwordx4 v[0:3], v195, s[20:21] nt
	s_add_u32 s20, s20, 0x5800
	s_addc_u32 s21, s21, 0
	global_load_dwordx4 v[4:7], v195, s[20:21] nt
	s_add_u32 s20, s20, 0x5800
	s_addc_u32 s21, s21, 0
	global_load_dwordx4 v[8:11], v195, s[20:21] nt
	s_add_u32 s20, s20, 0x5800
	s_addc_u32 s21, s21, 0
	global_load_dwordx4 v[12:15], v195, s[20:21] nt
	s_add_u32 s20, s20, 0x5800
	s_addc_u32 s21, s21, 0
	global_load_dwordx4 v[16:19], v195, s[20:21] nt
	s_add_u32 s20, s20, 0x5800
	s_addc_u32 s21, s21, 0
	global_load_dwordx4 v[20:23], v195, s[20:21] nt
	s_add_u32 s20, s20, 0x5800
	s_addc_u32 s21, s21, 0
	global_load_dwordx4 v[24:27], v195, s[20:21] nt
	s_add_u32 s20, s20, 0x5800
	s_addc_u32 s21, s21, 0
	global_load_dwordx4 v[28:31], v195, s[20:21] nt
	s_add_u32 s20, s20, 0x5800
	s_addc_u32 s21, s21, 0
	global_load_dwordx4 v[32:35], v195, s[20:21] nt
	s_add_u32 s20, s20, 0x5800
	s_addc_u32 s21, s21, 0
	global_load_dwordx4 v[36:39], v195, s[20:21] nt
	s_add_u32 s20, s20, 0x5800
	s_addc_u32 s21, s21, 0
	global_load_dwordx4 v[40:43], v195, s[20:21] nt
	s_add_u32 s20, s20, 0x5800
	s_addc_u32 s21, s21, 0
	global_load_dwordx4 v[44:47], v195, s[20:21] nt
	s_add_u32 s20, s20, 0x5800
	s_addc_u32 s21, s21, 0
	global_load_dwordx4 v[48:51], v195, s[20:21] nt
	s_add_u32 s20, s20, 0x5800
	s_addc_u32 s21, s21, 0
	global_load_dwordx4 v[52:55], v195, s[20:21] nt
	s_add_u32 s20, s20, 0x5800
	s_addc_u32 s21, s21, 0
	global_load_dwordx4 v[56:59], v195, s[20:21] nt
	s_add_u32 s20, s20, 0x5800
	s_addc_u32 s21, s21, 0
	global_load_dwordx4 v[60:63], v195, s[20:21] nt
	global_load_dwordx4 v[144:147], v199, s[36:37] offset:0
	global_load_dwordx4 v[148:151], v199, s[36:37] offset:16
	global_load_dwordx4 v[152:155], v199, s[36:37] offset:32
	global_load_dwordx4 v[156:159], v199, s[36:37] offset:48
	global_load_dwordx4 v[80:83], v195, s[22:23] nt
	s_add_u32 s22, s22, 0x5800
	s_addc_u32 s23, s23, 0
	global_load_dwordx4 v[84:87], v195, s[22:23] nt
	s_add_u32 s22, s22, 0x5800
	s_addc_u32 s23, s23, 0
	global_load_dwordx4 v[88:91], v195, s[22:23] nt
	s_add_u32 s22, s22, 0x5800
	s_addc_u32 s23, s23, 0
	global_load_dwordx4 v[92:95], v195, s[22:23] nt
	s_add_u32 s22, s22, 0x5800
	s_addc_u32 s23, s23, 0
	global_load_dwordx4 v[96:99], v195, s[22:23] nt
	s_add_u32 s22, s22, 0x5800
	s_addc_u32 s23, s23, 0
	global_load_dwordx4 v[100:103], v195, s[22:23] nt
	s_add_u32 s22, s22, 0x5800
	s_addc_u32 s23, s23, 0
	global_load_dwordx4 v[104:107], v195, s[22:23] nt
	s_add_u32 s22, s22, 0x5800
	s_addc_u32 s23, s23, 0
	global_load_dwordx4 v[108:111], v195, s[22:23] nt
	s_add_u32 s22, s22, 0x5800
	s_addc_u32 s23, s23, 0
	global_load_dwordx4 v[112:115], v195, s[22:23] nt
	s_add_u32 s22, s22, 0x5800
	s_addc_u32 s23, s23, 0
	global_load_dwordx4 v[116:119], v195, s[22:23] nt
	s_add_u32 s22, s22, 0x5800
	s_addc_u32 s23, s23, 0
	global_load_dwordx4 v[120:123], v195, s[22:23] nt
	s_add_u32 s22, s22, 0x5800
	s_addc_u32 s23, s23, 0
	global_load_dwordx4 v[124:127], v195, s[22:23] nt
	s_add_u32 s22, s22, 0x5800
	s_addc_u32 s23, s23, 0
	global_load_dwordx4 v[128:131], v195, s[22:23] nt
	s_add_u32 s22, s22, 0x5800
	s_addc_u32 s23, s23, 0
	global_load_dwordx4 v[132:135], v195, s[22:23] nt
	s_add_u32 s22, s22, 0x5800
	s_addc_u32 s23, s23, 0
	global_load_dwordx4 v[136:139], v195, s[22:23] nt
	s_add_u32 s22, s22, 0x5800
	s_addc_u32 s23, s23, 0
	global_load_dwordx4 v[140:143], v195, s[22:23] nt
	s_cmpk_lt_u32 s2, 0xc0
	s_cbranch_scc0 .Lp4_copy_two
	s_add_i32 s44, s2, 512
	s_cmpk_ge_u32 s44, 0x160
	s_cselect_b32 s45, 1, 0
	s_mul_i32 s67, s45, 0x160
	s_sub_i32 s44, s44, s67
	s_mul_i32 s67, s44, 2979
	s_lshr_b32 s67, s67, 16
	s_mul_i32 s69, s67, 22
	s_sub_i32 s69, s44, s69
	s_lshl_b32 s67, s67, 7
	s_cmp_eq_u32 s45, 0
	s_cselect_b32 s24, s60, s62
	s_cselect_b32 s25, s61, s63
	s_mul_i32 s76, s67, 0x5800
	s_lshl_b32 s44, s69, 10
	s_add_i32 s76, s76, s44
	s_lshl_b32 s44, s91, 7
	s_add_i32 s76, s76, s44
	s_add_u32 s24, s24, s76
	s_addc_u32 s25, s25, 0
	s_lshl_b32 s44, s67, 2
	s_add_u32 s38, s40, s44
	s_addc_u32 s39, s41, 0
	s_lshl_b32 s44, s69, 20
	s_lshl_b32 s45, s45, 18
	s_add_i32 s44, s44, s45
	s_add_i32 s44, s44, s67
	s_add_i32 s44, s44, s77
	s_add_u32 s30, s50, s44
	s_addc_u32 s31, s51, 0
	s_add_u32 s30, s30, 0x6300000
	s_addc_u32 s31, s31, 0
	s_waitcnt vmcnt(20)
	v_mul_f32_e32 v64, v64, v192
	v_mul_f32_e32 v65, v65, v192
	v_mul_f32_e32 v66, v66, v192
	v_mul_f32_e32 v67, v67, v192
	v_mul_f32_e32 v68, v68, v192
	v_mul_f32_e32 v69, v69, v192
	v_mul_f32_e32 v70, v70, v192
	v_mul_f32_e32 v71, v71, v192
	v_mul_f32_e32 v72, v72, v192
	v_mul_f32_e32 v73, v73, v192
	v_mul_f32_e32 v74, v74, v192
	v_mul_f32_e32 v75, v75, v192
	v_mul_f32_e32 v76, v76, v192
	v_mul_f32_e32 v77, v77, v192
	v_mul_f32_e32 v78, v78, v192
	v_mul_f32_e32 v79, v79, v192
	v_pk_mul_f32 v[0:1], v[0:1], v[64:65] op_sel_hi:[1,0]
	v_pk_mul_f32 v[2:3], v[2:3], v[64:65] op_sel_hi:[1,0]
	v_pk_mul_f32 v[4:5], v[4:5], v[64:65] op_sel:[0,1] op_sel_hi:[1,1]
	v_pk_mul_f32 v[6:7], v[6:7], v[64:65] op_sel:[0,1] op_sel_hi:[1,1]
	v_pk_mul_f32 v[8:9], v[8:9], v[66:67] op_sel_hi:[1,0]
	v_pk_mul_f32 v[10:11], v[10:11], v[66:67] op_sel_hi:[1,0]
	v_pk_mul_f32 v[12:13], v[12:13], v[66:67] op_sel:[0,1] op_sel_hi:[1,1]
	v_pk_mul_f32 v[14:15], v[14:15], v[66:67] op_sel:[0,1] op_sel_hi:[1,1]
	v_pk_mul_f32 v[16:17], v[16:17], v[68:69] op_sel_hi:[1,0]
	v_pk_mul_f32 v[18:19], v[18:19], v[68:69] op_sel_hi:[1,0]
	v_pk_mul_f32 v[20:21], v[20:21], v[68:69] op_sel:[0,1] op_sel_hi:[1,1]
	v_pk_mul_f32 v[22:23], v[22:23], v[68:69] op_sel:[0,1] op_sel_hi:[1,1]
	v_pk_mul_f32 v[24:25], v[24:25], v[70:71] op_sel_hi:[1,0]
	v_pk_mul_f32 v[26:27], v[26:27], v[70:71] op_sel_hi:[1,0]
	v_pk_mul_f32 v[28:29], v[28:29], v[70:71] op_sel:[0,1] op_sel_hi:[1,1]
	v_pk_mul_f32 v[30:31], v[30:31], v[70:71] op_sel:[0,1] op_sel_hi:[1,1]
	v_pk_mul_f32 v[32:33], v[32:33], v[72:73] op_sel_hi:[1,0]
	v_pk_mul_f32 v[34:35], v[34:35], v[72:73] op_sel_hi:[1,0]
	v_pk_mul_f32 v[36:37], v[36:37], v[72:73] op_sel:[0,1] op_sel_hi:[1,1]
	v_pk_mul_f32 v[38:39], v[38:39], v[72:73] op_sel:[0,1] op_sel_hi:[1,1]
	v_pk_mul_f32 v[40:41], v[40:41], v[74:75] op_sel_hi:[1,0]
	v_pk_mul_f32 v[42:43], v[42:43], v[74:75] op_sel_hi:[1,0]
	v_pk_mul_f32 v[44:45], v[44:45], v[74:75] op_sel:[0,1] op_sel_hi:[1,1]
	v_pk_mul_f32 v[46:47], v[46:47], v[74:75] op_sel:[0,1] op_sel_hi:[1,1]
	v_pk_mul_f32 v[48:49], v[48:49], v[76:77] op_sel_hi:[1,0]
	v_pk_mul_f32 v[50:51], v[50:51], v[76:77] op_sel_hi:[1,0]
	v_pk_mul_f32 v[52:53], v[52:53], v[76:77] op_sel:[0,1] op_sel_hi:[1,1]
	v_pk_mul_f32 v[54:55], v[54:55], v[76:77] op_sel:[0,1] op_sel_hi:[1,1]
	v_pk_mul_f32 v[56:57], v[56:57], v[78:79] op_sel_hi:[1,0]
	v_pk_mul_f32 v[58:59], v[58:59], v[78:79] op_sel_hi:[1,0]
	v_pk_mul_f32 v[60:61], v[60:61], v[78:79] op_sel:[0,1] op_sel_hi:[1,1]
	v_pk_mul_f32 v[62:63], v[62:63], v[78:79] op_sel:[0,1] op_sel_hi:[1,1]
	v_med3_f32 v0, v0, v194, v193
	v_med3_f32 v1, v1, v194, v193
	v_med3_f32 v2, v2, v194, v193
	v_med3_f32 v3, v3, v194, v193
	v_med3_f32 v4, v4, v194, v193
	v_med3_f32 v5, v5, v194, v193
	v_med3_f32 v6, v6, v194, v193
	v_med3_f32 v7, v7, v194, v193
	v_med3_f32 v8, v8, v194, v193
	v_med3_f32 v9, v9, v194, v193
	v_med3_f32 v10, v10, v194, v193
	v_med3_f32 v11, v11, v194, v193
	v_med3_f32 v12, v12, v194, v193
	v_med3_f32 v13, v13, v194, v193
	v_med3_f32 v14, v14, v194, v193
	v_med3_f32 v15, v15, v194, v193
	v_med3_f32 v16, v16, v194, v193
	v_med3_f32 v17, v17, v194, v193
	v_med3_f32 v18, v18, v194, v193
	v_med3_f32 v19, v19, v194, v193
	v_med3_f32 v20, v20, v194, v193
	v_med3_f32 v21, v21, v194, v193
	v_med3_f32 v22, v22, v194, v193
	v_med3_f32 v23, v23, v194, v193
	v_med3_f32 v24, v24, v194, v193
	v_med3_f32 v25, v25, v194, v193
	v_med3_f32 v26, v26, v194, v193
	v_med3_f32 v27, v27, v194, v193
	v_med3_f32 v28, v28, v194, v193
	v_med3_f32 v29, v29, v194, v193
	v_med3_f32 v30, v30, v194, v193
	v_med3_f32 v31, v31, v194, v193
	v_med3_f32 v32, v32, v194, v193
	v_med3_f32 v33, v33, v194, v193
	v_med3_f32 v34, v34, v194, v193
	v_med3_f32 v35, v35, v194, v193
	v_med3_f32 v36, v36, v194, v193
	v_med3_f32 v37, v37, v194, v193
	v_med3_f32 v38, v38, v194, v193
	v_med3_f32 v39, v39, v194, v193
	v_med3_f32 v40, v40, v194, v193
	v_med3_f32 v41, v41, v194, v193
	v_med3_f32 v42, v42, v194, v193
	v_med3_f32 v43, v43, v194, v193
	v_med3_f32 v44, v44, v194, v193
	v_med3_f32 v45, v45, v194, v193
	v_med3_f32 v46, v46, v194, v193
	v_med3_f32 v47, v47, v194, v193
	v_med3_f32 v48, v48, v194, v193
	v_med3_f32 v49, v49, v194, v193
	v_med3_f32 v50, v50, v194, v193
	v_med3_f32 v51, v51, v194, v193
	v_med3_f32 v52, v52, v194, v193
	v_med3_f32 v53, v53, v194, v193
	v_med3_f32 v54, v54, v194, v193
	v_med3_f32 v55, v55, v194, v193
	v_med3_f32 v56, v56, v194, v193
	v_med3_f32 v57, v57, v194, v193
	v_med3_f32 v58, v58, v194, v193
	v_med3_f32 v59, v59, v194, v193
	v_med3_f32 v60, v60, v194, v193
	v_med3_f32 v61, v61, v194, v193
	v_med3_f32 v62, v62, v194, v193
	v_med3_f32 v63, v63, v194, v193
	v_cvt_pk_fp8_f32 v160, v0, v4
	v_cvt_pk_fp8_f32 v161, v16, v20
	v_cvt_pk_fp8_f32 v162, v32, v36
	v_cvt_pk_fp8_f32 v163, v48, v52
	v_cvt_pk_fp8_f32 v164, v1, v5
	v_cvt_pk_fp8_f32 v165, v17, v21
	v_cvt_pk_fp8_f32 v166, v33, v37
	v_cvt_pk_fp8_f32 v167, v49, v53
	v_cvt_pk_fp8_f32 v168, v2, v6
	v_cvt_pk_fp8_f32 v169, v18, v22
	v_cvt_pk_fp8_f32 v170, v34, v38
	v_cvt_pk_fp8_f32 v171, v50, v54
	v_cvt_pk_fp8_f32 v172, v3, v7
	v_cvt_pk_fp8_f32 v173, v19, v23
	v_cvt_pk_fp8_f32 v174, v35, v39
	v_cvt_pk_fp8_f32 v175, v51, v55
	v_cvt_pk_fp8_f32 v160, v8, v12 op_sel:[0,0,1]
	v_cvt_pk_fp8_f32 v161, v24, v28 op_sel:[0,0,1]
	v_cvt_pk_fp8_f32 v162, v40, v44 op_sel:[0,0,1]
	v_cvt_pk_fp8_f32 v163, v56, v60 op_sel:[0,0,1]
	v_cvt_pk_fp8_f32 v164, v9, v13 op_sel:[0,0,1]
	v_cvt_pk_fp8_f32 v165, v25, v29 op_sel:[0,0,1]
	v_cvt_pk_fp8_f32 v166, v41, v45 op_sel:[0,0,1]
	v_cvt_pk_fp8_f32 v167, v57, v61 op_sel:[0,0,1]
	v_cvt_pk_fp8_f32 v168, v10, v14 op_sel:[0,0,1]
	v_cvt_pk_fp8_f32 v169, v26, v30 op_sel:[0,0,1]
	v_cvt_pk_fp8_f32 v170, v42, v46 op_sel:[0,0,1]
	v_cvt_pk_fp8_f32 v171, v58, v62 op_sel:[0,0,1]
	v_cvt_pk_fp8_f32 v172, v11, v15 op_sel:[0,0,1]
	v_cvt_pk_fp8_f32 v173, v27, v31 op_sel:[0,0,1]
	v_cvt_pk_fp8_f32 v174, v43, v47 op_sel:[0,0,1]
	v_cvt_pk_fp8_f32 v175, v59, v63 op_sel:[0,0,1]
	s_nop 0
	ds_bpermute_b32 v176, v198, v160
	ds_bpermute_b32 v177, v198, v161
	ds_bpermute_b32 v178, v198, v162
	ds_bpermute_b32 v179, v198, v163
	ds_bpermute_b32 v180, v198, v164
	ds_bpermute_b32 v181, v198, v165
	ds_bpermute_b32 v182, v198, v166
	ds_bpermute_b32 v183, v198, v167
	ds_bpermute_b32 v184, v198, v168
	ds_bpermute_b32 v185, v198, v169
	ds_bpermute_b32 v186, v198, v170
	ds_bpermute_b32 v187, v198, v171
	ds_bpermute_b32 v188, v198, v172
	ds_bpermute_b32 v189, v198, v173
	ds_bpermute_b32 v190, v198, v174
	ds_bpermute_b32 v191, v198, v175
	s_waitcnt lgkmcnt(0)
	global_store_dwordx4 v196, v[176:179], s[26:27]
	global_store_dwordx4 v196, v[180:183], s[26:27] offset:2048
	global_store_dwordx4 v197, v[184:187], s[26:27]
	global_store_dwordx4 v197, v[188:191], s[26:27] offset:2048
	global_load_dwordx4 v[64:67], v199, s[38:39] offset:0
	global_load_dwordx4 v[68:71], v199, s[38:39] offset:16
	global_load_dwordx4 v[72:75], v199, s[38:39] offset:32
	global_load_dwordx4 v[76:79], v199, s[38:39] offset:48
	global_load_dwordx4 v[0:3], v195, s[24:25] nt
	s_add_u32 s24, s24, 0x5800
	s_addc_u32 s25, s25, 0
	global_load_dwordx4 v[4:7], v195, s[24:25] nt
	s_add_u32 s24, s24, 0x5800
	s_addc_u32 s25, s25, 0
	global_load_dwordx4 v[8:11], v195, s[24:25] nt
	s_add_u32 s24, s24, 0x5800
	s_addc_u32 s25, s25, 0
	global_load_dwordx4 v[12:15], v195, s[24:25] nt
	s_add_u32 s24, s24, 0x5800
	s_addc_u32 s25, s25, 0
	global_load_dwordx4 v[16:19], v195, s[24:25] nt
	s_add_u32 s24, s24, 0x5800
	s_addc_u32 s25, s25, 0
	global_load_dwordx4 v[20:23], v195, s[24:25] nt
	s_add_u32 s24, s24, 0x5800
	s_addc_u32 s25, s25, 0
	global_load_dwordx4 v[24:27], v195, s[24:25] nt
	s_add_u32 s24, s24, 0x5800
	s_addc_u32 s25, s25, 0
	global_load_dwordx4 v[28:31], v195, s[24:25] nt
	s_add_u32 s24, s24, 0x5800
	s_addc_u32 s25, s25, 0
	global_load_dwordx4 v[32:35], v195, s[24:25] nt
	s_add_u32 s24, s24, 0x5800
	s_addc_u32 s25, s25, 0
	global_load_dwordx4 v[36:39], v195, s[24:25] nt
	s_add_u32 s24, s24, 0x5800
	s_addc_u32 s25, s25, 0
	global_load_dwordx4 v[40:43], v195, s[24:25] nt
	s_add_u32 s24, s24, 0x5800
	s_addc_u32 s25, s25, 0
	global_load_dwordx4 v[44:47], v195, s[24:25] nt
	s_add_u32 s24, s24, 0x5800
	s_addc_u32 s25, s25, 0
	global_load_dwordx4 v[48:51], v195, s[24:25] nt
	s_add_u32 s24, s24, 0x5800
	s_addc_u32 s25, s25, 0
	global_load_dwordx4 v[52:55], v195, s[24:25] nt
	s_add_u32 s24, s24, 0x5800
	s_addc_u32 s25, s25, 0
	global_load_dwordx4 v[56:59], v195, s[24:25] nt
	s_add_u32 s24, s24, 0x5800
	s_addc_u32 s25, s25, 0
	global_load_dwordx4 v[60:63], v195, s[24:25] nt
	s_waitcnt vmcnt(24)
	v_mul_f32_e32 v144, v144, v192
	v_mul_f32_e32 v145, v145, v192
	v_mul_f32_e32 v146, v146, v192
	v_mul_f32_e32 v147, v147, v192
	v_mul_f32_e32 v148, v148, v192
	v_mul_f32_e32 v149, v149, v192
	v_mul_f32_e32 v150, v150, v192
	v_mul_f32_e32 v151, v151, v192
	v_mul_f32_e32 v152, v152, v192
	v_mul_f32_e32 v153, v153, v192
	v_mul_f32_e32 v154, v154, v192
	v_mul_f32_e32 v155, v155, v192
	v_mul_f32_e32 v156, v156, v192
	v_mul_f32_e32 v157, v157, v192
	v_mul_f32_e32 v158, v158, v192
	v_mul_f32_e32 v159, v159, v192
	v_pk_mul_f32 v[80:81], v[80:81], v[144:145] op_sel_hi:[1,0]
	v_pk_mul_f32 v[82:83], v[82:83], v[144:145] op_sel_hi:[1,0]
	v_pk_mul_f32 v[84:85], v[84:85], v[144:145] op_sel:[0,1] op_sel_hi:[1,1]
	v_pk_mul_f32 v[86:87], v[86:87], v[144:145] op_sel:[0,1] op_sel_hi:[1,1]
	v_pk_mul_f32 v[88:89], v[88:89], v[146:147] op_sel_hi:[1,0]
	v_pk_mul_f32 v[90:91], v[90:91], v[146:147] op_sel_hi:[1,0]
	v_pk_mul_f32 v[92:93], v[92:93], v[146:147] op_sel:[0,1] op_sel_hi:[1,1]
	v_pk_mul_f32 v[94:95], v[94:95], v[146:147] op_sel:[0,1] op_sel_hi:[1,1]
	v_pk_mul_f32 v[96:97], v[96:97], v[148:149] op_sel_hi:[1,0]
	v_pk_mul_f32 v[98:99], v[98:99], v[148:149] op_sel_hi:[1,0]
	v_pk_mul_f32 v[100:101], v[100:101], v[148:149] op_sel:[0,1] op_sel_hi:[1,1]
	v_pk_mul_f32 v[102:103], v[102:103], v[148:149] op_sel:[0,1] op_sel_hi:[1,1]
	v_pk_mul_f32 v[104:105], v[104:105], v[150:151] op_sel_hi:[1,0]
	v_pk_mul_f32 v[106:107], v[106:107], v[150:151] op_sel_hi:[1,0]
	v_pk_mul_f32 v[108:109], v[108:109], v[150:151] op_sel:[0,1] op_sel_hi:[1,1]
	v_pk_mul_f32 v[110:111], v[110:111], v[150:151] op_sel:[0,1] op_sel_hi:[1,1]
	v_pk_mul_f32 v[112:113], v[112:113], v[152:153] op_sel_hi:[1,0]
	v_pk_mul_f32 v[114:115], v[114:115], v[152:153] op_sel_hi:[1,0]
	v_pk_mul_f32 v[116:117], v[116:117], v[152:153] op_sel:[0,1] op_sel_hi:[1,1]
	v_pk_mul_f32 v[118:119], v[118:119], v[152:153] op_sel:[0,1] op_sel_hi:[1,1]
	v_pk_mul_f32 v[120:121], v[120:121], v[154:155] op_sel_hi:[1,0]
	v_pk_mul_f32 v[122:123], v[122:123], v[154:155] op_sel_hi:[1,0]
	v_pk_mul_f32 v[124:125], v[124:125], v[154:155] op_sel:[0,1] op_sel_hi:[1,1]
	v_pk_mul_f32 v[126:127], v[126:127], v[154:155] op_sel:[0,1] op_sel_hi:[1,1]
	v_pk_mul_f32 v[128:129], v[128:129], v[156:157] op_sel_hi:[1,0]
	v_pk_mul_f32 v[130:131], v[130:131], v[156:157] op_sel_hi:[1,0]
	v_pk_mul_f32 v[132:133], v[132:133], v[156:157] op_sel:[0,1] op_sel_hi:[1,1]
	v_pk_mul_f32 v[134:135], v[134:135], v[156:157] op_sel:[0,1] op_sel_hi:[1,1]
	v_pk_mul_f32 v[136:137], v[136:137], v[158:159] op_sel_hi:[1,0]
	v_pk_mul_f32 v[138:139], v[138:139], v[158:159] op_sel_hi:[1,0]
	v_pk_mul_f32 v[140:141], v[140:141], v[158:159] op_sel:[0,1] op_sel_hi:[1,1]
	v_pk_mul_f32 v[142:143], v[142:143], v[158:159] op_sel:[0,1] op_sel_hi:[1,1]
	v_med3_f32 v80, v80, v194, v193
	v_med3_f32 v81, v81, v194, v193
	v_med3_f32 v82, v82, v194, v193
	v_med3_f32 v83, v83, v194, v193
	v_med3_f32 v84, v84, v194, v193
	v_med3_f32 v85, v85, v194, v193
	v_med3_f32 v86, v86, v194, v193
	v_med3_f32 v87, v87, v194, v193
	v_med3_f32 v88, v88, v194, v193
	v_med3_f32 v89, v89, v194, v193
	v_med3_f32 v90, v90, v194, v193
	v_med3_f32 v91, v91, v194, v193
	v_med3_f32 v92, v92, v194, v193
	v_med3_f32 v93, v93, v194, v193
	v_med3_f32 v94, v94, v194, v193
	v_med3_f32 v95, v95, v194, v193
	v_med3_f32 v96, v96, v194, v193
	v_med3_f32 v97, v97, v194, v193
	v_med3_f32 v98, v98, v194, v193
	v_med3_f32 v99, v99, v194, v193
	v_med3_f32 v100, v100, v194, v193
	v_med3_f32 v101, v101, v194, v193
	v_med3_f32 v102, v102, v194, v193
	v_med3_f32 v103, v103, v194, v193
	v_med3_f32 v104, v104, v194, v193
	v_med3_f32 v105, v105, v194, v193
	v_med3_f32 v106, v106, v194, v193
	v_med3_f32 v107, v107, v194, v193
	v_med3_f32 v108, v108, v194, v193
	v_med3_f32 v109, v109, v194, v193
	v_med3_f32 v110, v110, v194, v193
	v_med3_f32 v111, v111, v194, v193
	v_med3_f32 v112, v112, v194, v193
	v_med3_f32 v113, v113, v194, v193
	v_med3_f32 v114, v114, v194, v193
	v_med3_f32 v115, v115, v194, v193
	v_med3_f32 v116, v116, v194, v193
	v_med3_f32 v117, v117, v194, v193
	v_med3_f32 v118, v118, v194, v193
	v_med3_f32 v119, v119, v194, v193
	v_med3_f32 v120, v120, v194, v193
	v_med3_f32 v121, v121, v194, v193
	v_med3_f32 v122, v122, v194, v193
	v_med3_f32 v123, v123, v194, v193
	v_med3_f32 v124, v124, v194, v193
	v_med3_f32 v125, v125, v194, v193
	v_med3_f32 v126, v126, v194, v193
	v_med3_f32 v127, v127, v194, v193
	v_med3_f32 v128, v128, v194, v193
	v_med3_f32 v129, v129, v194, v193
	v_med3_f32 v130, v130, v194, v193
	v_med3_f32 v131, v131, v194, v193
	v_med3_f32 v132, v132, v194, v193
	v_med3_f32 v133, v133, v194, v193
	v_med3_f32 v134, v134, v194, v193
	v_med3_f32 v135, v135, v194, v193
	v_med3_f32 v136, v136, v194, v193
	v_med3_f32 v137, v137, v194, v193
	v_med3_f32 v138, v138, v194, v193
	v_med3_f32 v139, v139, v194, v193
	v_med3_f32 v140, v140, v194, v193
	v_med3_f32 v141, v141, v194, v193
	v_med3_f32 v142, v142, v194, v193
	v_med3_f32 v143, v143, v194, v193
	v_cvt_pk_fp8_f32 v160, v80, v84
	v_cvt_pk_fp8_f32 v161, v96, v100
	v_cvt_pk_fp8_f32 v162, v112, v116
	v_cvt_pk_fp8_f32 v163, v128, v132
	v_cvt_pk_fp8_f32 v164, v81, v85
	v_cvt_pk_fp8_f32 v165, v97, v101
	v_cvt_pk_fp8_f32 v166, v113, v117
	v_cvt_pk_fp8_f32 v167, v129, v133
	v_cvt_pk_fp8_f32 v168, v82, v86
	v_cvt_pk_fp8_f32 v169, v98, v102
	v_cvt_pk_fp8_f32 v170, v114, v118
	v_cvt_pk_fp8_f32 v171, v130, v134
	v_cvt_pk_fp8_f32 v172, v83, v87
	v_cvt_pk_fp8_f32 v173, v99, v103
	v_cvt_pk_fp8_f32 v174, v115, v119
	v_cvt_pk_fp8_f32 v175, v131, v135
	v_cvt_pk_fp8_f32 v160, v88, v92 op_sel:[0,0,1]
	v_cvt_pk_fp8_f32 v161, v104, v108 op_sel:[0,0,1]
	v_cvt_pk_fp8_f32 v162, v120, v124 op_sel:[0,0,1]
	v_cvt_pk_fp8_f32 v163, v136, v140 op_sel:[0,0,1]
	v_cvt_pk_fp8_f32 v164, v89, v93 op_sel:[0,0,1]
	v_cvt_pk_fp8_f32 v165, v105, v109 op_sel:[0,0,1]
	v_cvt_pk_fp8_f32 v166, v121, v125 op_sel:[0,0,1]
	v_cvt_pk_fp8_f32 v167, v137, v141 op_sel:[0,0,1]
	v_cvt_pk_fp8_f32 v168, v90, v94 op_sel:[0,0,1]
	v_cvt_pk_fp8_f32 v169, v106, v110 op_sel:[0,0,1]
	v_cvt_pk_fp8_f32 v170, v122, v126 op_sel:[0,0,1]
	v_cvt_pk_fp8_f32 v171, v138, v142 op_sel:[0,0,1]
	v_cvt_pk_fp8_f32 v172, v91, v95 op_sel:[0,0,1]
	v_cvt_pk_fp8_f32 v173, v107, v111 op_sel:[0,0,1]
	v_cvt_pk_fp8_f32 v174, v123, v127 op_sel:[0,0,1]
	v_cvt_pk_fp8_f32 v175, v139, v143 op_sel:[0,0,1]
	s_nop 0
	ds_bpermute_b32 v176, v198, v160
	ds_bpermute_b32 v177, v198, v161
	ds_bpermute_b32 v178, v198, v162
	ds_bpermute_b32 v179, v198, v163
	ds_bpermute_b32 v180, v198, v164
	ds_bpermute_b32 v181, v198, v165
	ds_bpermute_b32 v182, v198, v166
	ds_bpermute_b32 v183, v198, v167
	ds_bpermute_b32 v184, v198, v168
	ds_bpermute_b32 v185, v198, v169
	ds_bpermute_b32 v186, v198, v170
	ds_bpermute_b32 v187, v198, v171
	ds_bpermute_b32 v188, v198, v172
	ds_bpermute_b32 v189, v198, v173
	ds_bpermute_b32 v190, v198, v174
	ds_bpermute_b32 v191, v198, v175
	s_waitcnt lgkmcnt(0)
	global_store_dwordx4 v196, v[176:179], s[28:29]
	global_store_dwordx4 v196, v[180:183], s[28:29] offset:2048
	global_store_dwordx4 v197, v[184:187], s[28:29]
	global_store_dwordx4 v197, v[188:191], s[28:29] offset:2048
	s_waitcnt vmcnt(4)
	v_mul_f32_e32 v64, v64, v192
	v_mul_f32_e32 v65, v65, v192
	v_mul_f32_e32 v66, v66, v192
	v_mul_f32_e32 v67, v67, v192
	v_mul_f32_e32 v68, v68, v192
	v_mul_f32_e32 v69, v69, v192
	v_mul_f32_e32 v70, v70, v192
	v_mul_f32_e32 v71, v71, v192
	v_mul_f32_e32 v72, v72, v192
	v_mul_f32_e32 v73, v73, v192
	v_mul_f32_e32 v74, v74, v192
	v_mul_f32_e32 v75, v75, v192
	v_mul_f32_e32 v76, v76, v192
	v_mul_f32_e32 v77, v77, v192
	v_mul_f32_e32 v78, v78, v192
	v_mul_f32_e32 v79, v79, v192
	v_pk_mul_f32 v[0:1], v[0:1], v[64:65] op_sel_hi:[1,0]
	v_pk_mul_f32 v[2:3], v[2:3], v[64:65] op_sel_hi:[1,0]
	v_pk_mul_f32 v[4:5], v[4:5], v[64:65] op_sel:[0,1] op_sel_hi:[1,1]
	v_pk_mul_f32 v[6:7], v[6:7], v[64:65] op_sel:[0,1] op_sel_hi:[1,1]
	v_pk_mul_f32 v[8:9], v[8:9], v[66:67] op_sel_hi:[1,0]
	v_pk_mul_f32 v[10:11], v[10:11], v[66:67] op_sel_hi:[1,0]
	v_pk_mul_f32 v[12:13], v[12:13], v[66:67] op_sel:[0,1] op_sel_hi:[1,1]
	v_pk_mul_f32 v[14:15], v[14:15], v[66:67] op_sel:[0,1] op_sel_hi:[1,1]
	v_pk_mul_f32 v[16:17], v[16:17], v[68:69] op_sel_hi:[1,0]
	v_pk_mul_f32 v[18:19], v[18:19], v[68:69] op_sel_hi:[1,0]
	v_pk_mul_f32 v[20:21], v[20:21], v[68:69] op_sel:[0,1] op_sel_hi:[1,1]
	v_pk_mul_f32 v[22:23], v[22:23], v[68:69] op_sel:[0,1] op_sel_hi:[1,1]
	v_pk_mul_f32 v[24:25], v[24:25], v[70:71] op_sel_hi:[1,0]
	v_pk_mul_f32 v[26:27], v[26:27], v[70:71] op_sel_hi:[1,0]
	v_pk_mul_f32 v[28:29], v[28:29], v[70:71] op_sel:[0,1] op_sel_hi:[1,1]
	v_pk_mul_f32 v[30:31], v[30:31], v[70:71] op_sel:[0,1] op_sel_hi:[1,1]
	v_pk_mul_f32 v[32:33], v[32:33], v[72:73] op_sel_hi:[1,0]
	v_pk_mul_f32 v[34:35], v[34:35], v[72:73] op_sel_hi:[1,0]
	v_pk_mul_f32 v[36:37], v[36:37], v[72:73] op_sel:[0,1] op_sel_hi:[1,1]
	v_pk_mul_f32 v[38:39], v[38:39], v[72:73] op_sel:[0,1] op_sel_hi:[1,1]
	v_pk_mul_f32 v[40:41], v[40:41], v[74:75] op_sel_hi:[1,0]
	v_pk_mul_f32 v[42:43], v[42:43], v[74:75] op_sel_hi:[1,0]
	v_pk_mul_f32 v[44:45], v[44:45], v[74:75] op_sel:[0,1] op_sel_hi:[1,1]
	v_pk_mul_f32 v[46:47], v[46:47], v[74:75] op_sel:[0,1] op_sel_hi:[1,1]
	v_pk_mul_f32 v[48:49], v[48:49], v[76:77] op_sel_hi:[1,0]
	v_pk_mul_f32 v[50:51], v[50:51], v[76:77] op_sel_hi:[1,0]
	v_pk_mul_f32 v[52:53], v[52:53], v[76:77] op_sel:[0,1] op_sel_hi:[1,1]
	v_pk_mul_f32 v[54:55], v[54:55], v[76:77] op_sel:[0,1] op_sel_hi:[1,1]
	v_pk_mul_f32 v[56:57], v[56:57], v[78:79] op_sel_hi:[1,0]
	v_pk_mul_f32 v[58:59], v[58:59], v[78:79] op_sel_hi:[1,0]
	v_pk_mul_f32 v[60:61], v[60:61], v[78:79] op_sel:[0,1] op_sel_hi:[1,1]
	v_pk_mul_f32 v[62:63], v[62:63], v[78:79] op_sel:[0,1] op_sel_hi:[1,1]
	v_med3_f32 v0, v0, v194, v193
	v_med3_f32 v1, v1, v194, v193
	v_med3_f32 v2, v2, v194, v193
	v_med3_f32 v3, v3, v194, v193
	v_med3_f32 v4, v4, v194, v193
	v_med3_f32 v5, v5, v194, v193
	v_med3_f32 v6, v6, v194, v193
	v_med3_f32 v7, v7, v194, v193
	v_med3_f32 v8, v8, v194, v193
	v_med3_f32 v9, v9, v194, v193
	v_med3_f32 v10, v10, v194, v193
	v_med3_f32 v11, v11, v194, v193
	v_med3_f32 v12, v12, v194, v193
	v_med3_f32 v13, v13, v194, v193
	v_med3_f32 v14, v14, v194, v193
	v_med3_f32 v15, v15, v194, v193
	v_med3_f32 v16, v16, v194, v193
	v_med3_f32 v17, v17, v194, v193
	v_med3_f32 v18, v18, v194, v193
	v_med3_f32 v19, v19, v194, v193
	v_med3_f32 v20, v20, v194, v193
	v_med3_f32 v21, v21, v194, v193
	v_med3_f32 v22, v22, v194, v193
	v_med3_f32 v23, v23, v194, v193
	v_med3_f32 v24, v24, v194, v193
	v_med3_f32 v25, v25, v194, v193
	v_med3_f32 v26, v26, v194, v193
	v_med3_f32 v27, v27, v194, v193
	v_med3_f32 v28, v28, v194, v193
	v_med3_f32 v29, v29, v194, v193
	v_med3_f32 v30, v30, v194, v193
	v_med3_f32 v31, v31, v194, v193
	v_med3_f32 v32, v32, v194, v193
	v_med3_f32 v33, v33, v194, v193
	v_med3_f32 v34, v34, v194, v193
	v_med3_f32 v35, v35, v194, v193
	v_med3_f32 v36, v36, v194, v193
	v_med3_f32 v37, v37, v194, v193
	v_med3_f32 v38, v38, v194, v193
	v_med3_f32 v39, v39, v194, v193
	v_med3_f32 v40, v40, v194, v193
	v_med3_f32 v41, v41, v194, v193
	v_med3_f32 v42, v42, v194, v193
	v_med3_f32 v43, v43, v194, v193
	v_med3_f32 v44, v44, v194, v193
	v_med3_f32 v45, v45, v194, v193
	v_med3_f32 v46, v46, v194, v193
	v_med3_f32 v47, v47, v194, v193
	v_med3_f32 v48, v48, v194, v193
	v_med3_f32 v49, v49, v194, v193
	v_med3_f32 v50, v50, v194, v193
	v_med3_f32 v51, v51, v194, v193
	v_med3_f32 v52, v52, v194, v193
	v_med3_f32 v53, v53, v194, v193
	v_med3_f32 v54, v54, v194, v193
	v_med3_f32 v55, v55, v194, v193
	v_med3_f32 v56, v56, v194, v193
	v_med3_f32 v57, v57, v194, v193
	v_med3_f32 v58, v58, v194, v193
	v_med3_f32 v59, v59, v194, v193
	v_med3_f32 v60, v60, v194, v193
	v_med3_f32 v61, v61, v194, v193
	v_med3_f32 v62, v62, v194, v193
	v_med3_f32 v63, v63, v194, v193
	v_cvt_pk_fp8_f32 v160, v0, v4
	v_cvt_pk_fp8_f32 v161, v16, v20
	v_cvt_pk_fp8_f32 v162, v32, v36
	v_cvt_pk_fp8_f32 v163, v48, v52
	v_cvt_pk_fp8_f32 v164, v1, v5
	v_cvt_pk_fp8_f32 v165, v17, v21
	v_cvt_pk_fp8_f32 v166, v33, v37
	v_cvt_pk_fp8_f32 v167, v49, v53
	v_cvt_pk_fp8_f32 v168, v2, v6
	v_cvt_pk_fp8_f32 v169, v18, v22
	v_cvt_pk_fp8_f32 v170, v34, v38
	v_cvt_pk_fp8_f32 v171, v50, v54
	v_cvt_pk_fp8_f32 v172, v3, v7
	v_cvt_pk_fp8_f32 v173, v19, v23
	v_cvt_pk_fp8_f32 v174, v35, v39
	v_cvt_pk_fp8_f32 v175, v51, v55
	v_cvt_pk_fp8_f32 v160, v8, v12 op_sel:[0,0,1]
	v_cvt_pk_fp8_f32 v161, v24, v28 op_sel:[0,0,1]
	v_cvt_pk_fp8_f32 v162, v40, v44 op_sel:[0,0,1]
	v_cvt_pk_fp8_f32 v163, v56, v60 op_sel:[0,0,1]
	v_cvt_pk_fp8_f32 v164, v9, v13 op_sel:[0,0,1]
	v_cvt_pk_fp8_f32 v165, v25, v29 op_sel:[0,0,1]
	v_cvt_pk_fp8_f32 v166, v41, v45 op_sel:[0,0,1]
	v_cvt_pk_fp8_f32 v167, v57, v61 op_sel:[0,0,1]
	v_cvt_pk_fp8_f32 v168, v10, v14 op_sel:[0,0,1]
	v_cvt_pk_fp8_f32 v169, v26, v30 op_sel:[0,0,1]
	v_cvt_pk_fp8_f32 v170, v42, v46 op_sel:[0,0,1]
	v_cvt_pk_fp8_f32 v171, v58, v62 op_sel:[0,0,1]
	v_cvt_pk_fp8_f32 v172, v11, v15 op_sel:[0,0,1]
	v_cvt_pk_fp8_f32 v173, v27, v31 op_sel:[0,0,1]
	v_cvt_pk_fp8_f32 v174, v43, v47 op_sel:[0,0,1]
	v_cvt_pk_fp8_f32 v175, v59, v63 op_sel:[0,0,1]
	s_nop 0
	ds_bpermute_b32 v176, v198, v160
	ds_bpermute_b32 v177, v198, v161
	ds_bpermute_b32 v178, v198, v162
	ds_bpermute_b32 v179, v198, v163
	ds_bpermute_b32 v180, v198, v164
	ds_bpermute_b32 v181, v198, v165
	ds_bpermute_b32 v182, v198, v166
	ds_bpermute_b32 v183, v198, v167
	ds_bpermute_b32 v184, v198, v168
	ds_bpermute_b32 v185, v198, v169
	ds_bpermute_b32 v186, v198, v170
	ds_bpermute_b32 v187, v198, v171
	ds_bpermute_b32 v188, v198, v172
	ds_bpermute_b32 v189, v198, v173
	ds_bpermute_b32 v190, v198, v174
	ds_bpermute_b32 v191, v198, v175
	s_waitcnt lgkmcnt(0)
	global_store_dwordx4 v196, v[176:179], s[30:31]
	global_store_dwordx4 v196, v[180:183], s[30:31] offset:2048
	global_store_dwordx4 v197, v[184:187], s[30:31]
	global_store_dwordx4 v197, v[188:191], s[30:31] offset:2048
	s_branch .Lp4_copy_done
.Lp4_copy_two:
	s_waitcnt vmcnt(20)
	v_mul_f32_e32 v64, v64, v192
	v_mul_f32_e32 v65, v65, v192
	v_mul_f32_e32 v66, v66, v192
	v_mul_f32_e32 v67, v67, v192
	v_mul_f32_e32 v68, v68, v192
	v_mul_f32_e32 v69, v69, v192
	v_mul_f32_e32 v70, v70, v192
	v_mul_f32_e32 v71, v71, v192
	v_mul_f32_e32 v72, v72, v192
	v_mul_f32_e32 v73, v73, v192
	v_mul_f32_e32 v74, v74, v192
	v_mul_f32_e32 v75, v75, v192
	v_mul_f32_e32 v76, v76, v192
	v_mul_f32_e32 v77, v77, v192
	v_mul_f32_e32 v78, v78, v192
	v_mul_f32_e32 v79, v79, v192
	v_pk_mul_f32 v[0:1], v[0:1], v[64:65] op_sel_hi:[1,0]
	v_pk_mul_f32 v[2:3], v[2:3], v[64:65] op_sel_hi:[1,0]
	v_pk_mul_f32 v[4:5], v[4:5], v[64:65] op_sel:[0,1] op_sel_hi:[1,1]
	v_pk_mul_f32 v[6:7], v[6:7], v[64:65] op_sel:[0,1] op_sel_hi:[1,1]
	v_pk_mul_f32 v[8:9], v[8:9], v[66:67] op_sel_hi:[1,0]
	v_pk_mul_f32 v[10:11], v[10:11], v[66:67] op_sel_hi:[1,0]
	v_pk_mul_f32 v[12:13], v[12:13], v[66:67] op_sel:[0,1] op_sel_hi:[1,1]
	v_pk_mul_f32 v[14:15], v[14:15], v[66:67] op_sel:[0,1] op_sel_hi:[1,1]
	v_pk_mul_f32 v[16:17], v[16:17], v[68:69] op_sel_hi:[1,0]
	v_pk_mul_f32 v[18:19], v[18:19], v[68:69] op_sel_hi:[1,0]
	v_pk_mul_f32 v[20:21], v[20:21], v[68:69] op_sel:[0,1] op_sel_hi:[1,1]
	v_pk_mul_f32 v[22:23], v[22:23], v[68:69] op_sel:[0,1] op_sel_hi:[1,1]
	v_pk_mul_f32 v[24:25], v[24:25], v[70:71] op_sel_hi:[1,0]
	v_pk_mul_f32 v[26:27], v[26:27], v[70:71] op_sel_hi:[1,0]
	v_pk_mul_f32 v[28:29], v[28:29], v[70:71] op_sel:[0,1] op_sel_hi:[1,1]
	v_pk_mul_f32 v[30:31], v[30:31], v[70:71] op_sel:[0,1] op_sel_hi:[1,1]
	v_pk_mul_f32 v[32:33], v[32:33], v[72:73] op_sel_hi:[1,0]
	v_pk_mul_f32 v[34:35], v[34:35], v[72:73] op_sel_hi:[1,0]
	v_pk_mul_f32 v[36:37], v[36:37], v[72:73] op_sel:[0,1] op_sel_hi:[1,1]
	v_pk_mul_f32 v[38:39], v[38:39], v[72:73] op_sel:[0,1] op_sel_hi:[1,1]
	v_pk_mul_f32 v[40:41], v[40:41], v[74:75] op_sel_hi:[1,0]
	v_pk_mul_f32 v[42:43], v[42:43], v[74:75] op_sel_hi:[1,0]
	v_pk_mul_f32 v[44:45], v[44:45], v[74:75] op_sel:[0,1] op_sel_hi:[1,1]
	v_pk_mul_f32 v[46:47], v[46:47], v[74:75] op_sel:[0,1] op_sel_hi:[1,1]
	v_pk_mul_f32 v[48:49], v[48:49], v[76:77] op_sel_hi:[1,0]
	v_pk_mul_f32 v[50:51], v[50:51], v[76:77] op_sel_hi:[1,0]
	v_pk_mul_f32 v[52:53], v[52:53], v[76:77] op_sel:[0,1] op_sel_hi:[1,1]
	v_pk_mul_f32 v[54:55], v[54:55], v[76:77] op_sel:[0,1] op_sel_hi:[1,1]
	v_pk_mul_f32 v[56:57], v[56:57], v[78:79] op_sel_hi:[1,0]
	v_pk_mul_f32 v[58:59], v[58:59], v[78:79] op_sel_hi:[1,0]
	v_pk_mul_f32 v[60:61], v[60:61], v[78:79] op_sel:[0,1] op_sel_hi:[1,1]
	v_pk_mul_f32 v[62:63], v[62:63], v[78:79] op_sel:[0,1] op_sel_hi:[1,1]
	v_med3_f32 v0, v0, v194, v193
	v_med3_f32 v1, v1, v194, v193
	v_med3_f32 v2, v2, v194, v193
	v_med3_f32 v3, v3, v194, v193
	v_med3_f32 v4, v4, v194, v193
	v_med3_f32 v5, v5, v194, v193
	v_med3_f32 v6, v6, v194, v193
	v_med3_f32 v7, v7, v194, v193
	v_med3_f32 v8, v8, v194, v193
	v_med3_f32 v9, v9, v194, v193
	v_med3_f32 v10, v10, v194, v193
	v_med3_f32 v11, v11, v194, v193
	v_med3_f32 v12, v12, v194, v193
	v_med3_f32 v13, v13, v194, v193
	v_med3_f32 v14, v14, v194, v193
	v_med3_f32 v15, v15, v194, v193
	v_med3_f32 v16, v16, v194, v193
	v_med3_f32 v17, v17, v194, v193
	v_med3_f32 v18, v18, v194, v193
	v_med3_f32 v19, v19, v194, v193
	v_med3_f32 v20, v20, v194, v193
	v_med3_f32 v21, v21, v194, v193
	v_med3_f32 v22, v22, v194, v193
	v_med3_f32 v23, v23, v194, v193
	v_med3_f32 v24, v24, v194, v193
	v_med3_f32 v25, v25, v194, v193
	v_med3_f32 v26, v26, v194, v193
	v_med3_f32 v27, v27, v194, v193
	v_med3_f32 v28, v28, v194, v193
	v_med3_f32 v29, v29, v194, v193
	v_med3_f32 v30, v30, v194, v193
	v_med3_f32 v31, v31, v194, v193
	v_med3_f32 v32, v32, v194, v193
	v_med3_f32 v33, v33, v194, v193
	v_med3_f32 v34, v34, v194, v193
	v_med3_f32 v35, v35, v194, v193
	v_med3_f32 v36, v36, v194, v193
	v_med3_f32 v37, v37, v194, v193
	v_med3_f32 v38, v38, v194, v193
	v_med3_f32 v39, v39, v194, v193
	v_med3_f32 v40, v40, v194, v193
	v_med3_f32 v41, v41, v194, v193
	v_med3_f32 v42, v42, v194, v193
	v_med3_f32 v43, v43, v194, v193
	v_med3_f32 v44, v44, v194, v193
	v_med3_f32 v45, v45, v194, v193
	v_med3_f32 v46, v46, v194, v193
	v_med3_f32 v47, v47, v194, v193
	v_med3_f32 v48, v48, v194, v193
	v_med3_f32 v49, v49, v194, v193
	v_med3_f32 v50, v50, v194, v193
	v_med3_f32 v51, v51, v194, v193
	v_med3_f32 v52, v52, v194, v193
	v_med3_f32 v53, v53, v194, v193
	v_med3_f32 v54, v54, v194, v193
	v_med3_f32 v55, v55, v194, v193
	v_med3_f32 v56, v56, v194, v193
	v_med3_f32 v57, v57, v194, v193
	v_med3_f32 v58, v58, v194, v193
	v_med3_f32 v59, v59, v194, v193
	v_med3_f32 v60, v60, v194, v193
	v_med3_f32 v61, v61, v194, v193
	v_med3_f32 v62, v62, v194, v193
	v_med3_f32 v63, v63, v194, v193
	v_cvt_pk_fp8_f32 v160, v0, v4
	v_cvt_pk_fp8_f32 v161, v16, v20
	v_cvt_pk_fp8_f32 v162, v32, v36
	v_cvt_pk_fp8_f32 v163, v48, v52
	v_cvt_pk_fp8_f32 v164, v1, v5
	v_cvt_pk_fp8_f32 v165, v17, v21
	v_cvt_pk_fp8_f32 v166, v33, v37
	v_cvt_pk_fp8_f32 v167, v49, v53
	v_cvt_pk_fp8_f32 v168, v2, v6
	v_cvt_pk_fp8_f32 v169, v18, v22
	v_cvt_pk_fp8_f32 v170, v34, v38
	v_cvt_pk_fp8_f32 v171, v50, v54
	v_cvt_pk_fp8_f32 v172, v3, v7
	v_cvt_pk_fp8_f32 v173, v19, v23
	v_cvt_pk_fp8_f32 v174, v35, v39
	v_cvt_pk_fp8_f32 v175, v51, v55
	v_cvt_pk_fp8_f32 v160, v8, v12 op_sel:[0,0,1]
	v_cvt_pk_fp8_f32 v161, v24, v28 op_sel:[0,0,1]
	v_cvt_pk_fp8_f32 v162, v40, v44 op_sel:[0,0,1]
	v_cvt_pk_fp8_f32 v163, v56, v60 op_sel:[0,0,1]
	v_cvt_pk_fp8_f32 v164, v9, v13 op_sel:[0,0,1]
	v_cvt_pk_fp8_f32 v165, v25, v29 op_sel:[0,0,1]
	v_cvt_pk_fp8_f32 v166, v41, v45 op_sel:[0,0,1]
	v_cvt_pk_fp8_f32 v167, v57, v61 op_sel:[0,0,1]
	v_cvt_pk_fp8_f32 v168, v10, v14 op_sel:[0,0,1]
	v_cvt_pk_fp8_f32 v169, v26, v30 op_sel:[0,0,1]
	v_cvt_pk_fp8_f32 v170, v42, v46 op_sel:[0,0,1]
	v_cvt_pk_fp8_f32 v171, v58, v62 op_sel:[0,0,1]
	v_cvt_pk_fp8_f32 v172, v11, v15 op_sel:[0,0,1]
	v_cvt_pk_fp8_f32 v173, v27, v31 op_sel:[0,0,1]
	v_cvt_pk_fp8_f32 v174, v43, v47 op_sel:[0,0,1]
	v_cvt_pk_fp8_f32 v175, v59, v63 op_sel:[0,0,1]
	s_nop 0
	ds_bpermute_b32 v176, v198, v160
	ds_bpermute_b32 v177, v198, v161
	ds_bpermute_b32 v178, v198, v162
	ds_bpermute_b32 v179, v198, v163
	ds_bpermute_b32 v180, v198, v164
	ds_bpermute_b32 v181, v198, v165
	ds_bpermute_b32 v182, v198, v166
	ds_bpermute_b32 v183, v198, v167
	ds_bpermute_b32 v184, v198, v168
	ds_bpermute_b32 v185, v198, v169
	ds_bpermute_b32 v186, v198, v170
	ds_bpermute_b32 v187, v198, v171
	ds_bpermute_b32 v188, v198, v172
	ds_bpermute_b32 v189, v198, v173
	ds_bpermute_b32 v190, v198, v174
	ds_bpermute_b32 v191, v198, v175
	s_waitcnt lgkmcnt(0)
	global_store_dwordx4 v196, v[176:179], s[26:27]
	global_store_dwordx4 v196, v[180:183], s[26:27] offset:2048
	global_store_dwordx4 v197, v[184:187], s[26:27]
	global_store_dwordx4 v197, v[188:191], s[26:27] offset:2048
	s_waitcnt vmcnt(4)
	v_mul_f32_e32 v144, v144, v192
	v_mul_f32_e32 v145, v145, v192
	v_mul_f32_e32 v146, v146, v192
	v_mul_f32_e32 v147, v147, v192
	v_mul_f32_e32 v148, v148, v192
	v_mul_f32_e32 v149, v149, v192
	v_mul_f32_e32 v150, v150, v192
	v_mul_f32_e32 v151, v151, v192
	v_mul_f32_e32 v152, v152, v192
	v_mul_f32_e32 v153, v153, v192
	v_mul_f32_e32 v154, v154, v192
	v_mul_f32_e32 v155, v155, v192
	v_mul_f32_e32 v156, v156, v192
	v_mul_f32_e32 v157, v157, v192
	v_mul_f32_e32 v158, v158, v192
	v_mul_f32_e32 v159, v159, v192
	v_pk_mul_f32 v[80:81], v[80:81], v[144:145] op_sel_hi:[1,0]
	v_pk_mul_f32 v[82:83], v[82:83], v[144:145] op_sel_hi:[1,0]
	v_pk_mul_f32 v[84:85], v[84:85], v[144:145] op_sel:[0,1] op_sel_hi:[1,1]
	v_pk_mul_f32 v[86:87], v[86:87], v[144:145] op_sel:[0,1] op_sel_hi:[1,1]
	v_pk_mul_f32 v[88:89], v[88:89], v[146:147] op_sel_hi:[1,0]
	v_pk_mul_f32 v[90:91], v[90:91], v[146:147] op_sel_hi:[1,0]
	v_pk_mul_f32 v[92:93], v[92:93], v[146:147] op_sel:[0,1] op_sel_hi:[1,1]
	v_pk_mul_f32 v[94:95], v[94:95], v[146:147] op_sel:[0,1] op_sel_hi:[1,1]
	v_pk_mul_f32 v[96:97], v[96:97], v[148:149] op_sel_hi:[1,0]
	v_pk_mul_f32 v[98:99], v[98:99], v[148:149] op_sel_hi:[1,0]
	v_pk_mul_f32 v[100:101], v[100:101], v[148:149] op_sel:[0,1] op_sel_hi:[1,1]
	v_pk_mul_f32 v[102:103], v[102:103], v[148:149] op_sel:[0,1] op_sel_hi:[1,1]
	v_pk_mul_f32 v[104:105], v[104:105], v[150:151] op_sel_hi:[1,0]
	v_pk_mul_f32 v[106:107], v[106:107], v[150:151] op_sel_hi:[1,0]
	v_pk_mul_f32 v[108:109], v[108:109], v[150:151] op_sel:[0,1] op_sel_hi:[1,1]
	v_pk_mul_f32 v[110:111], v[110:111], v[150:151] op_sel:[0,1] op_sel_hi:[1,1]
	v_pk_mul_f32 v[112:113], v[112:113], v[152:153] op_sel_hi:[1,0]
	v_pk_mul_f32 v[114:115], v[114:115], v[152:153] op_sel_hi:[1,0]
	v_pk_mul_f32 v[116:117], v[116:117], v[152:153] op_sel:[0,1] op_sel_hi:[1,1]
	v_pk_mul_f32 v[118:119], v[118:119], v[152:153] op_sel:[0,1] op_sel_hi:[1,1]
	v_pk_mul_f32 v[120:121], v[120:121], v[154:155] op_sel_hi:[1,0]
	v_pk_mul_f32 v[122:123], v[122:123], v[154:155] op_sel_hi:[1,0]
	v_pk_mul_f32 v[124:125], v[124:125], v[154:155] op_sel:[0,1] op_sel_hi:[1,1]
	v_pk_mul_f32 v[126:127], v[126:127], v[154:155] op_sel:[0,1] op_sel_hi:[1,1]
	v_pk_mul_f32 v[128:129], v[128:129], v[156:157] op_sel_hi:[1,0]
	v_pk_mul_f32 v[130:131], v[130:131], v[156:157] op_sel_hi:[1,0]
	v_pk_mul_f32 v[132:133], v[132:133], v[156:157] op_sel:[0,1] op_sel_hi:[1,1]
	v_pk_mul_f32 v[134:135], v[134:135], v[156:157] op_sel:[0,1] op_sel_hi:[1,1]
	v_pk_mul_f32 v[136:137], v[136:137], v[158:159] op_sel_hi:[1,0]
	v_pk_mul_f32 v[138:139], v[138:139], v[158:159] op_sel_hi:[1,0]
	v_pk_mul_f32 v[140:141], v[140:141], v[158:159] op_sel:[0,1] op_sel_hi:[1,1]
	v_pk_mul_f32 v[142:143], v[142:143], v[158:159] op_sel:[0,1] op_sel_hi:[1,1]
	v_med3_f32 v80, v80, v194, v193
	v_med3_f32 v81, v81, v194, v193
	v_med3_f32 v82, v82, v194, v193
	v_med3_f32 v83, v83, v194, v193
	v_med3_f32 v84, v84, v194, v193
	v_med3_f32 v85, v85, v194, v193
	v_med3_f32 v86, v86, v194, v193
	v_med3_f32 v87, v87, v194, v193
	v_med3_f32 v88, v88, v194, v193
	v_med3_f32 v89, v89, v194, v193
	v_med3_f32 v90, v90, v194, v193
	v_med3_f32 v91, v91, v194, v193
	v_med3_f32 v92, v92, v194, v193
	v_med3_f32 v93, v93, v194, v193
	v_med3_f32 v94, v94, v194, v193
	v_med3_f32 v95, v95, v194, v193
	v_med3_f32 v96, v96, v194, v193
	v_med3_f32 v97, v97, v194, v193
	v_med3_f32 v98, v98, v194, v193
	v_med3_f32 v99, v99, v194, v193
	v_med3_f32 v100, v100, v194, v193
	v_med3_f32 v101, v101, v194, v193
	v_med3_f32 v102, v102, v194, v193
	v_med3_f32 v103, v103, v194, v193
	v_med3_f32 v104, v104, v194, v193
	v_med3_f32 v105, v105, v194, v193
	v_med3_f32 v106, v106, v194, v193
	v_med3_f32 v107, v107, v194, v193
	v_med3_f32 v108, v108, v194, v193
	v_med3_f32 v109, v109, v194, v193
	v_med3_f32 v110, v110, v194, v193
	v_med3_f32 v111, v111, v194, v193
	v_med3_f32 v112, v112, v194, v193
	v_med3_f32 v113, v113, v194, v193
	v_med3_f32 v114, v114, v194, v193
	v_med3_f32 v115, v115, v194, v193
	v_med3_f32 v116, v116, v194, v193
	v_med3_f32 v117, v117, v194, v193
	v_med3_f32 v118, v118, v194, v193
	v_med3_f32 v119, v119, v194, v193
	v_med3_f32 v120, v120, v194, v193
	v_med3_f32 v121, v121, v194, v193
	v_med3_f32 v122, v122, v194, v193
	v_med3_f32 v123, v123, v194, v193
	v_med3_f32 v124, v124, v194, v193
	v_med3_f32 v125, v125, v194, v193
	v_med3_f32 v126, v126, v194, v193
	v_med3_f32 v127, v127, v194, v193
	v_med3_f32 v128, v128, v194, v193
	v_med3_f32 v129, v129, v194, v193
	v_med3_f32 v130, v130, v194, v193
	v_med3_f32 v131, v131, v194, v193
	v_med3_f32 v132, v132, v194, v193
	v_med3_f32 v133, v133, v194, v193
	v_med3_f32 v134, v134, v194, v193
	v_med3_f32 v135, v135, v194, v193
	v_med3_f32 v136, v136, v194, v193
	v_med3_f32 v137, v137, v194, v193
	v_med3_f32 v138, v138, v194, v193
	v_med3_f32 v139, v139, v194, v193
	v_med3_f32 v140, v140, v194, v193
	v_med3_f32 v141, v141, v194, v193
	v_med3_f32 v142, v142, v194, v193
	v_med3_f32 v143, v143, v194, v193
	v_cvt_pk_fp8_f32 v160, v80, v84
	v_cvt_pk_fp8_f32 v161, v96, v100
	v_cvt_pk_fp8_f32 v162, v112, v116
	v_cvt_pk_fp8_f32 v163, v128, v132
	v_cvt_pk_fp8_f32 v164, v81, v85
	v_cvt_pk_fp8_f32 v165, v97, v101
	v_cvt_pk_fp8_f32 v166, v113, v117
	v_cvt_pk_fp8_f32 v167, v129, v133
	v_cvt_pk_fp8_f32 v168, v82, v86
	v_cvt_pk_fp8_f32 v169, v98, v102
	v_cvt_pk_fp8_f32 v170, v114, v118
	v_cvt_pk_fp8_f32 v171, v130, v134
	v_cvt_pk_fp8_f32 v172, v83, v87
	v_cvt_pk_fp8_f32 v173, v99, v103
	v_cvt_pk_fp8_f32 v174, v115, v119
	v_cvt_pk_fp8_f32 v175, v131, v135
	v_cvt_pk_fp8_f32 v160, v88, v92 op_sel:[0,0,1]
	v_cvt_pk_fp8_f32 v161, v104, v108 op_sel:[0,0,1]
	v_cvt_pk_fp8_f32 v162, v120, v124 op_sel:[0,0,1]
	v_cvt_pk_fp8_f32 v163, v136, v140 op_sel:[0,0,1]
	v_cvt_pk_fp8_f32 v164, v89, v93 op_sel:[0,0,1]
	v_cvt_pk_fp8_f32 v165, v105, v109 op_sel:[0,0,1]
	v_cvt_pk_fp8_f32 v166, v121, v125 op_sel:[0,0,1]
	v_cvt_pk_fp8_f32 v167, v137, v141 op_sel:[0,0,1]
	v_cvt_pk_fp8_f32 v168, v90, v94 op_sel:[0,0,1]
	v_cvt_pk_fp8_f32 v169, v106, v110 op_sel:[0,0,1]
	v_cvt_pk_fp8_f32 v170, v122, v126 op_sel:[0,0,1]
	v_cvt_pk_fp8_f32 v171, v138, v142 op_sel:[0,0,1]
	v_cvt_pk_fp8_f32 v172, v91, v95 op_sel:[0,0,1]
	v_cvt_pk_fp8_f32 v173, v107, v111 op_sel:[0,0,1]
	v_cvt_pk_fp8_f32 v174, v123, v127 op_sel:[0,0,1]
	v_cvt_pk_fp8_f32 v175, v139, v143 op_sel:[0,0,1]
	s_nop 0
	ds_bpermute_b32 v176, v198, v160
	ds_bpermute_b32 v177, v198, v161
	ds_bpermute_b32 v178, v198, v162
	ds_bpermute_b32 v179, v198, v163
	ds_bpermute_b32 v180, v198, v164
	ds_bpermute_b32 v181, v198, v165
	ds_bpermute_b32 v182, v198, v166
	ds_bpermute_b32 v183, v198, v167
	ds_bpermute_b32 v184, v198, v168
	ds_bpermute_b32 v185, v198, v169
	ds_bpermute_b32 v186, v198, v170
	ds_bpermute_b32 v187, v198, v171
	ds_bpermute_b32 v188, v198, v172
	ds_bpermute_b32 v189, v198, v173
	ds_bpermute_b32 v190, v198, v174
	ds_bpermute_b32 v191, v198, v175
	s_waitcnt lgkmcnt(0)
	global_store_dwordx4 v196, v[176:179], s[28:29]
	global_store_dwordx4 v196, v[180:183], s[28:29] offset:2048
	global_store_dwordx4 v197, v[184:187], s[28:29]
	global_store_dwordx4 v197, v[188:191], s[28:29] offset:2048
.Lp4_copy_done:
	s_cmp_eq_u32 s98, 1
	s_cbranch_scc1 .LBB0_877
.Lp4_att_entry:
	s_barrier
	s_mov_b64 exec, -1
	s_add_u32 s74, s50, 0x10200000
	s_addc_u32 s75, s51, 0
	s_cmpk_gt_i32 s2, 0x1ff
	s_cbranch_scc1 .LBB0_867
	s_load_dwordx2 s[96:97], s[0:1], 0x58
	s_load_dwordx2 s[78:79], s[0:1], 0x40
	v_lshl_add_u32 v0, s91, 6, v234
	v_and_b32_e32 v1, 15, v234
	v_lshrrev_b32_e32 v2, 4, v234
	s_movk_i32 s69, 0x88
	v_cmp_gt_u32_e64 s[80:81], s69, v0
	v_lshlrev_b32_e32 v226, 4, v0
	v_add_u32_e32 v227, 0x2000, v226
	v_lshrrev_b32_e32 v3, 4, v0
	v_mul_u32_u24_e32 v3, 0x110, v3
	v_and_b32_e32 v252, 15, v0
	v_lshl_add_u32 v228, v252, 4, v3
	v_lshrrev_b32_e32 v3, 3, v0
	v_and_b32_e32 v252, 7, v0
	v_lshlrev_b32_e32 v252, 4, v252
	v_lshl_add_u32 v229, v3, 14, v252
	v_add_u32_e32 v230, 0x100000, v229
	v_mul_u32_u24_e32 v3, 0x90, v3
	v_add_u32_e32 v231, v3, v252
	s_cmp_eq_u32 s92, 0
	s_cselect_b32 s29, 0, 8
	s_cmp_gt_u32 s92, 1
	s_cselect_b32 s29, 24, s29
	s_cmp_eq_u32 s92, 3
	s_cselect_b32 s29, 32, s29
	v_lshrrev_b32_e32 v3, 2, v1
	v_lshlrev_b32_e32 v3, 3, v3
	v_and_b32_e32 v252, 3, v1
	v_add3_u32 v3, v3, v252, s29
	v_mul_u32_u24_e32 v3, 0x110, v3
	v_lshl_add_u32 v232, v2, 4, v3
	v_mul_u32_u24_e32 v3, 0x90, v1
	v_lshl_add_u32 v252, v2, 3, s29
	v_lshl_add_u32 v233, v252, 1, v3
	v_lshlrev_b32_e32 v3, 8, v1
	v_lshl_add_u32 v235, v2, 4, v3
	v_lshlrev_b32_e32 v3, 12, v1
	v_lshl_add_u32 v236, v2, 3, v3
	v_lshlrev_b32_e32 v237, 4, v2
	v_xor_b32_e32 v238, 16, v234
	v_xor_b32_e32 v239, 32, v234
	v_lshlrev_b32_e32 v238, 2, v238
	v_lshlrev_b32_e32 v239, 2, v239
	v_lshl_add_u32 v3, s92, 4, v1
	v_subrev_u32_e32 v253, 8, v3
	v_max_i32_e32 v253, 0, v253
	v_min_i32_e32 v253, 48, v253
	v_add_u32_e32 v254, 16, v253
	v_add_u32_e32 v255, 0, v252
	v_cmp_ge_i32_e64 s[4:5], v255, v253
	v_cmp_lt_i32_e64 s[44:45], v255, v254
	v_sub_u32_e32 v255, v255, v3
	v_add_u32_e32 v255, 15, v255
	s_and_b64 s[4:5], s[4:5], s[44:45]
	v_max_i32_e32 v255, 0, v255
	v_min_i32_e32 v255, 30, v255
	v_lshlrev_b32_e32 v240, 2, v255
	v_add_u32_e32 v255, 1, v252
	v_cmp_ge_i32_e64 s[6:7], v255, v253
	v_cmp_lt_i32_e64 s[44:45], v255, v254
	v_sub_u32_e32 v255, v255, v3
	v_add_u32_e32 v255, 15, v255
	s_and_b64 s[6:7], s[6:7], s[44:45]
	v_max_i32_e32 v255, 0, v255
	v_min_i32_e32 v255, 30, v255
	v_lshlrev_b32_e32 v241, 2, v255
	v_add_u32_e32 v255, 2, v252
	v_cmp_ge_i32_e64 s[8:9], v255, v253
	v_cmp_lt_i32_e64 s[44:45], v255, v254
	v_sub_u32_e32 v255, v255, v3
	v_add_u32_e32 v255, 15, v255
	s_and_b64 s[8:9], s[8:9], s[44:45]
	v_max_i32_e32 v255, 0, v255
	v_min_i32_e32 v255, 30, v255
	v_lshlrev_b32_e32 v242, 2, v255
	v_add_u32_e32 v255, 3, v252
	v_cmp_ge_i32_e64 s[10:11], v255, v253
	v_cmp_lt_i32_e64 s[44:45], v255, v254
	v_sub_u32_e32 v255, v255, v3
	v_add_u32_e32 v255, 15, v255
	s_and_b64 s[10:11], s[10:11], s[44:45]
	v_max_i32_e32 v255, 0, v255
	v_min_i32_e32 v255, 30, v255
	v_lshlrev_b32_e32 v243, 2, v255
	v_add_u32_e32 v255, 4, v252
	v_cmp_ge_i32_e64 s[12:13], v255, v253
	v_cmp_lt_i32_e64 s[44:45], v255, v254
	v_sub_u32_e32 v255, v255, v3
	v_add_u32_e32 v255, 15, v255
	s_and_b64 s[12:13], s[12:13], s[44:45]
	v_max_i32_e32 v255, 0, v255
	v_min_i32_e32 v255, 30, v255
	v_lshlrev_b32_e32 v244, 2, v255
	v_add_u32_e32 v255, 5, v252
	v_cmp_ge_i32_e64 s[14:15], v255, v253
	v_cmp_lt_i32_e64 s[44:45], v255, v254
	v_sub_u32_e32 v255, v255, v3
	v_add_u32_e32 v255, 15, v255
	s_and_b64 s[14:15], s[14:15], s[44:45]
	v_max_i32_e32 v255, 0, v255
	v_min_i32_e32 v255, 30, v255
	v_lshlrev_b32_e32 v245, 2, v255
	v_add_u32_e32 v255, 6, v252
	v_cmp_ge_i32_e64 s[16:17], v255, v253
	v_cmp_lt_i32_e64 s[44:45], v255, v254
	v_sub_u32_e32 v255, v255, v3
	v_add_u32_e32 v255, 15, v255
	s_and_b64 s[16:17], s[16:17], s[44:45]
	v_max_i32_e32 v255, 0, v255
	v_min_i32_e32 v255, 30, v255
	v_lshlrev_b32_e32 v246, 2, v255
	v_add_u32_e32 v255, 7, v252
	v_cmp_ge_i32_e64 s[18:19], v255, v253
	v_cmp_lt_i32_e64 s[44:45], v255, v254
	v_sub_u32_e32 v255, v255, v3
	v_add_u32_e32 v255, 15, v255
	s_and_b64 s[18:19], s[18:19], s[44:45]
	v_max_i32_e32 v255, 0, v255
	v_min_i32_e32 v255, 30, v255
	v_lshlrev_b32_e32 v247, 2, v255
	v_lshlrev_b32_e32 v2, 2, v0
	s_mov_b32 s20, s2
	s_waitcnt lgkmcnt(0)
	global_load_dword v92, v2, s[78:79]
	s_add_u32 s78, s78, 0x800
	s_addc_u32 s79, s79, 0
	global_load_dword v93, v2, s[78:79]
	s_add_u32 s78, s78, 0x800
	s_addc_u32 s79, s79, 0
	global_load_dword v94, v2, s[78:79]
	s_add_u32 s78, s78, 0x800
	s_addc_u32 s79, s79, 0
	global_load_dword v95, v2, s[78:79]
	s_add_u32 s78, s78, 0x800
	s_addc_u32 s79, s79, 0
	global_load_dword v96, v2, s[78:79]
	s_add_u32 s78, s78, 0x800
	s_addc_u32 s79, s79, 0
	global_load_dword v97, v2, s[78:79]
	s_add_u32 s78, s78, 0x800
	s_addc_u32 s79, s79, 0
	global_load_dword v98, v2, s[78:79]
	s_add_u32 s78, s78, 0x800
	s_addc_u32 s79, s79, 0
	s_and_saveexec_b64 s[44:45], s[80:81]
	global_load_dword v99, v2, s[78:79]
	s_mov_b64 exec, s[44:45]
	s_and_b32 s69, s20, 7
	s_lshr_b32 s76, s20, 8
	s_lshl_b32 s69, s69, 1
	s_add_i32 s69, s69, s76
	s_lshl_b32 s69, s69, 12
	s_bfe_u32 s76, s20, 0x50003
	s_lshl_b32 s76, s76, 1
	s_add_i32 s77, s76, -4
	s_max_i32 s77, s77, 0
	s_min_i32 s77, s77, 56
	s_add_i32 s83, s76, -3
	s_max_i32 s83, s83, 0
	s_min_i32 s83, s83, 56
	s_add_i32 s83, s83, 8
	s_sub_i32 s83, s83, s77
	s_add_i32 s76, s76, s88
	s_lshl_b32 s77, s77, 6
	s_add_i32 s77, s77, s69
	s_lshl_b32 s77, s77, 8
	s_add_u32 s34, s50, s77
	s_addc_u32 s35, s51, 0
	s_add_u32 s34, s34, 0xe200000
	s_addc_u32 s35, s35, 0
	s_lshl_b32 s76, s76, 6
	s_add_i32 s76, s76, s69
	s_lshl_b32 s77, s92, 4
	s_add_i32 s76, s76, s77
	s_lshl_b32 s76, s76, 8
	s_add_u32 s36, s50, s76
	s_addc_u32 s37, s51, 0
	s_add_u32 s36, s36, 0xd200000
	s_addc_u32 s37, s37, 0
	global_load_dwordx4 v[76:79], v235, s[36:37] offset:0
	global_load_dwordx4 v[80:83], v235, s[36:37] offset:64
	global_load_dwordx4 v[84:87], v235, s[36:37] offset:128
	global_load_dwordx4 v[88:91], v235, s[36:37] offset:192
	global_load_dwordx4 v[4:7], v226, s[34:35]
	global_load_dwordx4 v[8:11], v227, s[34:35]
	s_add_u32 s34, s34, 0x4000
	s_addc_u32 s35, s35, 0
	global_load_dwordx4 v[12:15], v226, s[34:35]
	global_load_dwordx4 v[16:19], v227, s[34:35]
	s_add_u32 s34, s34, 0x4000
	s_addc_u32 s35, s35, 0
	global_load_dwordx4 v[20:23], v226, s[34:35]
	global_load_dwordx4 v[24:27], v227, s[34:35]
	s_add_u32 s34, s34, 0x4000
	s_addc_u32 s35, s35, 0
	global_load_dwordx4 v[28:31], v226, s[34:35]
	global_load_dwordx4 v[32:35], v227, s[34:35]
	s_add_u32 s34, s34, 0x4000
	s_addc_u32 s35, s35, 0
	global_load_dwordx4 v[36:39], v226, s[34:35]
	global_load_dwordx4 v[40:43], v227, s[34:35]
	s_add_u32 s34, s34, 0x4000
	s_addc_u32 s35, s35, 0
	global_load_dwordx4 v[44:47], v226, s[34:35]
	global_load_dwordx4 v[48:51], v227, s[34:35]
	s_add_u32 s34, s34, 0x4000
	s_addc_u32 s35, s35, 0
	global_load_dwordx4 v[52:55], v226, s[34:35]
	global_load_dwordx4 v[56:59], v227, s[34:35]
	s_add_u32 s34, s34, 0x4000
	s_addc_u32 s35, s35, 0
	global_load_dwordx4 v[60:63], v226, s[34:35]
	global_load_dwordx4 v[64:67], v227, s[34:35]
	s_add_u32 s34, s34, 0x4000
	s_addc_u32 s35, s35, 0
	s_cmp_lt_u32 s83, 9
	s_cbranch_scc1 .Latt_k8_skip_p
	global_load_dwordx4 v[68:71], v226, s[34:35]
	global_load_dwordx4 v[72:75], v227, s[34:35]

	.amdhsa_kernel _Z6mk_fwd4Args
		.amdhsa_group_segment_fixed_size 0
		.amdhsa_private_segment_fixed_size 0
		.amdhsa_kernarg_size 448
		.amdhsa_user_sgpr_count 2
		.amdhsa_user_sgpr_dispatch_ptr 0
		.amdhsa_user_sgpr_queue_ptr 0
		.amdhsa_user_sgpr_kernarg_segment_ptr 1
		.amdhsa_user_sgpr_dispatch_id 0
		.amdhsa_user_sgpr_kernarg_preload_length 0
		.amdhsa_user_sgpr_kernarg_preload_offset 0
		.amdhsa_user_sgpr_private_segment_size 0
		.amdhsa_uses_dynamic_stack 0
		.amdhsa_enable_private_segment 0
		.amdhsa_system_sgpr_workgroup_id_x 1
		.amdhsa_system_sgpr_workgroup_id_y 0
		.amdhsa_system_sgpr_workgroup_id_z 0
		.amdhsa_system_sgpr_workgroup_info 0
		.amdhsa_system_vgpr_workitem_id 2
		.amdhsa_next_free_vgpr 256
		.amdhsa_next_free_sgpr 100
		.amdhsa_accum_offset 256
		.amdhsa_reserve_vcc 1
		.amdhsa_float_round_mode_32 0
		.amdhsa_float_round_mode_16_64 0
		.amdhsa_float_denorm_mode_32 3
		.amdhsa_float_denorm_mode_16_64 3
		.amdhsa_dx10_clamp 1
		.amdhsa_ieee_mode 1
		.amdhsa_fp16_overflow 0
		.amdhsa_tg_split 0
		.amdhsa_exception_fp_ieee_invalid_op 0
		.amdhsa_exception_fp_denorm_src 0
		.amdhsa_exception_fp_ieee_div_zero 0
		.amdhsa_exception_fp_ieee_overflow 0
		.amdhsa_exception_fp_ieee_underflow 0
		.amdhsa_exception_fp_ieee_inexact 0
		.amdhsa_exception_int_div_zero 0
	.end_amdhsa_kernel
